# as v150 plus: domain-barrier waits 0/1 and the grid barrier issue the L1 invalidate before the first poll (overlapped)
# baseline (speedup 1.0000x reference)
; __device__ __forceinline__ unsigned xb_ld(unsigned* p)              { return __hip_atomic_load(p, __ATOMIC_RELAXED, __HIP_MEMORY_SCOPE_AGENT); }
; __device__ __forceinline__ unsigned xb_add(unsigned* p, unsigned v) { return __hip_atomic_fetch_add(p, v, __ATOMIC_RELAXED, __HIP_MEMORY_SCOPE_AGENT); }
; #define XB_SPIN(cond, bar) do { unsigned _sp = 0; while (cond) { __builtin_amdgcn_s_sleep(1); \
;     if ((++_sp & 255u) == 0u) { if (xb_ld(&(bar)[XB_TMO])) break; if (_sp > XB_SPIN_CAP) { atomicAdd(&(bar)[XB_TMO], 1u); break; } } } } while (0)
; __device__ __forceinline__ void xcd_barrier(const XcdBarrier& b) {
;     ...
;         const unsigned old = xb_add(&bar[XB_XSUB(b.x)], 1u);
;         const unsigned gen = old / nloc;
;         if (old + 1u == (gen + 1u) * nloc) {
;             __builtin_amdgcn_fence(__ATOMIC_RELEASE, "agent");
;             asm volatile("s_waitcnt vmcnt(0)" ::: "memory");
;             const unsigned og = xb_add(&bar[XB_TOP], 1u);
;             const unsigned tg = og / nx;
;             if (og + 1u == (tg + 1u) * nx) xb_add(&bar[XB_TOPGEN], 1u);
;             else XB_SPIN(xb_ld(&bar[XB_TOPGEN]) == tg, bar);
;             __builtin_amdgcn_fence(__ATOMIC_ACQUIRE, "agent");
;             xb_add(&bar[XB_XGEN(b.x)], 1u);
;             asm volatile("s_waitcnt vmcnt(0)" ::: "memory");
;         } else {
;             XB_SPIN(xb_ld(&bar[XB_XGEN(b.x)]) == gen, bar);
;             __builtin_amdgcn_fence(__ATOMIC_ACQUIRE, "agent");
;             asm volatile("s_waitcnt vmcnt(0)" ::: "memory");
;         }
.LBB0_118:
	s_or_b64 exec, exec, s[6:7]
	v_cvt_f32_u32_e32 v4, v2
	s_waitcnt vmcnt(0)
	v_readfirstlane_b32 s4, v3
	v_sub_u32_e32 v3, 0, v2
	v_rcp_iflag_f32_e32 v4, v4
	v_add_u32_e32 v5, s4, v1
	v_mul_f32_e32 v4, 0x4f7ffffe, v4
	v_cvt_u32_f32_e32 v4, v4
	v_mul_lo_u32 v1, v3, v4
	v_mul_hi_u32 v1, v4, v1
	v_add_u32_e32 v1, v4, v1
	v_mul_hi_u32 v1, v5, v1
	v_mul_lo_u32 v3, v1, v2
	v_sub_u32_e32 v3, v5, v3
	v_add_u32_e32 v4, 1, v1
	v_cmp_ge_u32_e32 vcc, v3, v2
	s_nop 1
	v_cndmask_b32_e32 v1, v1, v4, vcc
	v_sub_u32_e32 v4, v3, v2
	v_cndmask_b32_e32 v3, v3, v4, vcc
	v_add_u32_e32 v4, 1, v1
	v_cmp_ge_u32_e32 vcc, v3, v2
	v_add_u32_e32 v3, 1, v5
	s_nop 0
	v_cndmask_b32_e32 v1, v1, v4, vcc
	v_mul_lo_u32 v4, v2, v1
	v_add_u32_e32 v2, v4, v2
	v_cmp_ne_u32_e32 vcc, v3, v2
	s_and_saveexec_b64 s[4:5], vcc
	s_xor_b64 s[4:5], exec, s[4:5]
	s_cbranch_execz .LBB0_132
	s_waitcnt lgkmcnt(0)
	buffer_inv sc1
	v_mov_b32_e32 v0, 0x2000
	global_load_dword v0, v0, s[2:3] offset:1024 sc1
	s_add_u32 s10, s2, 0x2400
	s_addc_u32 s11, s3, 0
	s_waitcnt vmcnt(0)
	v_cmp_eq_u32_e32 vcc, v0, v1
	s_and_saveexec_b64 s[6:7], vcc
	s_cbranch_execz .LBB0_131
	s_add_u32 s8, s34, 0xae00
	s_addc_u32 s9, s35, 0
	s_mov_b32 s36, 1
	s_mov_b64 s[12:13], 0
	v_mov_b32_e32 v0, 0
	s_branch .LBB0_122

; __device__ __forceinline__ unsigned xb_ld(unsigned* p)              { return __hip_atomic_load(p, __ATOMIC_RELAXED, __HIP_MEMORY_SCOPE_AGENT); }
; #define XB_SPIN(cond, bar) do { unsigned _sp = 0; while (cond) { __builtin_amdgcn_s_sleep(1); \
;     if ((++_sp & 255u) == 0u) { if (xb_ld(&(bar)[XB_TMO])) break; if (_sp > XB_SPIN_CAP) { atomicAdd(&(bar)[XB_TMO], 1u); break; } } } } while (0)
; __device__ __forceinline__ void xcd_barrier(const XcdBarrier& b) {
;     ...
;         } else {
;             XB_SPIN(xb_ld(&bar[XB_XGEN(b.x)]) == gen, bar);
;             __builtin_amdgcn_fence(__ATOMIC_ACQUIRE, "agent");
;             asm volatile("s_waitcnt vmcnt(0)" ::: "memory");
.LBB0_131:
	s_or_b64 exec, exec, s[6:7]
	s_waitcnt vmcnt(0)
	s_waitcnt vmcnt(0)

; __device__ __forceinline__ int lane_id() { int l; asm volatile("v_mbcnt_lo_u32_b32 %0, -1, 0\n\tv_mbcnt_hi_u32_b32 %0, -1, %0" : "=v"(l)); return l; }
; __device__ __forceinline__ unsigned pk2(float lo, float hi) { return f2bf(lo) | (f2bf(hi) << 16); }
; __device__ __forceinline__ unsigned xb_ld(unsigned* p)              { return __hip_atomic_load(p, __ATOMIC_RELAXED, __HIP_MEMORY_SCOPE_AGENT); }
; #define XB_SPIN(cond, bar) do { unsigned _sp = 0; while (cond) { __builtin_amdgcn_s_sleep(1); \
;     if ((++_sp & 255u) == 0u) { if (xb_ld(&(bar)[XB_TMO])) break; if (_sp > XB_SPIN_CAP) { atomicAdd(&(bar)[XB_TMO], 1u); break; } } } } while (0)
; __device__ __forceinline__ void xcd_wait(const XcdBarrier& b, unsigned use) {
;     if (b.w0 != 0 && lane_id() == 0) {
;         unsigned* bar = b.bar;
;         XB_SPIN(xb_ld(&bar[XB_TOPGEN]) <= use, bar);
;         __builtin_amdgcn_fence(__ATOMIC_ACQUIRE, "agent");
;         asm volatile("s_waitcnt vmcnt(0)" ::: "memory");
;     }
;     __syncthreads();
; __device__ __forceinline__ void prep_w_half(Frame& F) {
;     ...
; #pragma unroll
;     for (int j = 0; j < 8; ++j) { v2u w; w.x = pk2(pv[j].x, pv[j].y); w.y = pk2(pv[j].z, pv[j].w); pd[64 * j] = w; }
.LBB0_304:
	s_add_u32 s48, s34, 0x2a00000
	s_addc_u32 s49, s35, 0
	s_lshl_b32 s5, s6, 3
	s_add_u32 s5, s48, s5
	s_addc_u32 s6, s49, 0
	s_lshl_b64 s[0:1], s[0:1], 3
	s_add_u32 s0, s5, s0
	s_addc_u32 s1, s6, s1
	v_lshl_add_u64 v[32:33], v[32:33], 3, s[0:1]
	s_waitcnt vmcnt(7)
	v_bfe_u32 v34, v28, 16, 1
	s_movk_i32 s0, 0x7fff
	v_add3_u32 v28, v28, v34, s0
	v_bfe_u32 v34, v29, 16, 1
	v_lshrrev_b32_e32 v28, 16, v28
	v_add3_u32 v29, v29, v34, s0
	s_mov_b32 s1, 0xffff0000
	v_and_or_b32 v28, v29, s1, v28
	v_bfe_u32 v29, v30, 16, 1
	v_add3_u32 v29, v30, v29, s0
	v_bfe_u32 v30, v31, 16, 1
	v_lshrrev_b32_e32 v29, 16, v29
	v_add3_u32 v30, v31, v30, s0
	v_and_or_b32 v29, v30, s1, v29
	global_store_dwordx2 v[32:33], v[28:29], off
	s_waitcnt vmcnt(7)
	v_bfe_u32 v28, v24, 16, 1
	v_add3_u32 v24, v24, v28, s0
	v_bfe_u32 v28, v25, 16, 1
	v_lshrrev_b32_e32 v24, 16, v24
	v_add3_u32 v25, v25, v28, s0
	v_and_or_b32 v24, v25, s1, v24
	v_bfe_u32 v25, v26, 16, 1
	v_add3_u32 v25, v26, v25, s0
	v_bfe_u32 v26, v27, 16, 1
	v_lshrrev_b32_e32 v25, 16, v25
	v_add3_u32 v26, v27, v26, s0
	v_and_or_b32 v25, v26, s1, v25
	global_store_dwordx2 v[32:33], v[24:25], off offset:512
	s_waitcnt vmcnt(7)
	v_bfe_u32 v24, v20, 16, 1
	v_add3_u32 v20, v20, v24, s0
	v_bfe_u32 v24, v21, 16, 1
	v_lshrrev_b32_e32 v20, 16, v20
	v_add3_u32 v21, v21, v24, s0
	v_and_or_b32 v20, v21, s1, v20
	v_bfe_u32 v21, v22, 16, 1
	v_add3_u32 v21, v22, v21, s0
	v_bfe_u32 v22, v23, 16, 1
	v_lshrrev_b32_e32 v21, 16, v21
	v_add3_u32 v22, v23, v22, s0
	v_and_or_b32 v21, v22, s1, v21
	global_store_dwordx2 v[32:33], v[20:21], off offset:1024
	s_waitcnt vmcnt(7)
	v_bfe_u32 v20, v16, 16, 1
	v_add3_u32 v16, v16, v20, s0
	v_bfe_u32 v20, v17, 16, 1
	v_lshrrev_b32_e32 v16, 16, v16
	v_add3_u32 v17, v17, v20, s0
	v_and_or_b32 v16, v17, s1, v16
	v_bfe_u32 v17, v18, 16, 1
	v_add3_u32 v17, v18, v17, s0
	v_bfe_u32 v18, v19, 16, 1
	v_lshrrev_b32_e32 v17, 16, v17
	v_add3_u32 v18, v19, v18, s0
	v_and_or_b32 v17, v18, s1, v17
	global_store_dwordx2 v[32:33], v[16:17], off offset:1536
	s_waitcnt vmcnt(7)
	v_bfe_u32 v16, v12, 16, 1
	v_add3_u32 v12, v12, v16, s0
	v_bfe_u32 v16, v13, 16, 1
	v_lshrrev_b32_e32 v12, 16, v12
	v_add3_u32 v13, v13, v16, s0
	v_and_or_b32 v12, v13, s1, v12
	v_bfe_u32 v13, v14, 16, 1
	v_add3_u32 v13, v14, v13, s0
	v_bfe_u32 v14, v15, 16, 1
	v_lshrrev_b32_e32 v13, 16, v13
	v_add3_u32 v14, v15, v14, s0
	v_and_or_b32 v13, v14, s1, v13
	global_store_dwordx2 v[32:33], v[12:13], off offset:2048
	s_waitcnt vmcnt(7)
	v_bfe_u32 v12, v8, 16, 1
	v_add3_u32 v8, v8, v12, s0
	v_bfe_u32 v12, v9, 16, 1
	v_lshrrev_b32_e32 v8, 16, v8
	v_add3_u32 v9, v9, v12, s0
	v_and_or_b32 v8, v9, s1, v8
	v_bfe_u32 v9, v10, 16, 1
	v_add3_u32 v9, v10, v9, s0
	v_bfe_u32 v10, v11, 16, 1
	v_lshrrev_b32_e32 v9, 16, v9
	v_add3_u32 v10, v11, v10, s0
	v_and_or_b32 v9, v10, s1, v9
	global_store_dwordx2 v[32:33], v[8:9], off offset:2560
	s_waitcnt vmcnt(7)
	v_bfe_u32 v8, v4, 16, 1
	v_add3_u32 v4, v4, v8, s0
	v_bfe_u32 v8, v5, 16, 1
	v_lshrrev_b32_e32 v4, 16, v4
	v_add3_u32 v5, v5, v8, s0
	v_and_or_b32 v4, v5, s1, v4
	v_bfe_u32 v5, v6, 16, 1
	v_add3_u32 v5, v6, v5, s0
	v_bfe_u32 v6, v7, 16, 1
	v_lshrrev_b32_e32 v5, 16, v5
	v_add3_u32 v6, v7, v6, s0
	v_and_or_b32 v5, v6, s1, v5
	global_store_dwordx2 v[32:33], v[4:5], off offset:3072
	s_waitcnt vmcnt(7)
	v_bfe_u32 v4, v0, 16, 1
	v_add3_u32 v0, v0, v4, s0
	v_bfe_u32 v4, v1, 16, 1
	v_lshrrev_b32_e32 v0, 16, v0
	v_add3_u32 v1, v1, v4, s0
	v_and_or_b32 v0, v1, s1, v0
	v_bfe_u32 v1, v2, 16, 1
	v_add3_u32 v1, v2, v1, s0
	v_bfe_u32 v2, v3, 16, 1
	v_lshrrev_b32_e32 v1, 16, v1
	v_add3_u32 v2, v3, v2, s0
	v_and_or_b32 v1, v2, s1, v1
	v_cndmask_b32_e64 v2, 0, 1, s[2:3]
	v_cmp_ne_u32_e64 s[94:95], 1, v2
	s_andn2_b64 vcc, exec, s[2:3]
	global_store_dwordx2 v[32:33], v[0:1], off offset:3584
	s_cbranch_vccnz .LBB0_321
	v_mbcnt_lo_u32_b32 v0, -1, 0
	v_mbcnt_hi_u32_b32 v0, -1, v0
	s_nop 0
	v_cmp_eq_u32_e32 vcc, 0, v0
	s_and_saveexec_b64 s[2:3], vcc
	s_cbranch_execz .LBB0_320
	buffer_inv sc1
	v_mov_b32_e32 v0, 0x3000
	global_load_dword v0, v0, s[52:53] offset:1280 sc1
	s_add_u32 s6, s52, 0x3500
	s_addc_u32 s7, s53, 0
	s_waitcnt vmcnt(0)
	v_cmp_ne_u32_e32 vcc, 0, v0
	s_cbranch_vccnz .LBB0_319
	s_mov_b32 s0, 1
	v_mov_b32_e32 v0, 0
	s_branch .LBB0_309

; __device__ __forceinline__ int lane_id() { int l; asm volatile("v_mbcnt_lo_u32_b32 %0, -1, 0\n\tv_mbcnt_hi_u32_b32 %0, -1, %0" : "=v"(l)); return l; }
; __device__ __forceinline__ unsigned xb_ld(unsigned* p)              { return __hip_atomic_load(p, __ATOMIC_RELAXED, __HIP_MEMORY_SCOPE_AGENT); }
; #define XB_SPIN(cond, bar) do { unsigned _sp = 0; while (cond) { __builtin_amdgcn_s_sleep(1); \
;     if ((++_sp & 255u) == 0u) { if (xb_ld(&(bar)[XB_TMO])) break; if (_sp > XB_SPIN_CAP) { atomicAdd(&(bar)[XB_TMO], 1u); break; } } } } while (0)
; __device__ __forceinline__ void xcd_wait(const XcdBarrier& b, unsigned use) {
;     if (b.w0 != 0 && lane_id() == 0) {
;         unsigned* bar = b.bar;
;         XB_SPIN(xb_ld(&bar[XB_TOPGEN]) <= use, bar);
;         __builtin_amdgcn_fence(__ATOMIC_ACQUIRE, "agent");
;         asm volatile("s_waitcnt vmcnt(0)" ::: "memory");
;     }
.LBB0_319:
	s_waitcnt vmcnt(0)
	s_waitcnt vmcnt(0)

; __device__ __forceinline__ int lane_id() { int l; asm volatile("v_mbcnt_lo_u32_b32 %0, -1, 0\n\tv_mbcnt_hi_u32_b32 %0, -1, %0" : "=v"(l)); return l; }
; __device__ __forceinline__ unsigned xb_ld(unsigned* p)              { return __hip_atomic_load(p, __ATOMIC_RELAXED, __HIP_MEMORY_SCOPE_AGENT); }
; #define XB_SPIN(cond, bar) do { unsigned _sp = 0; while (cond) { __builtin_amdgcn_s_sleep(1); \
;     if ((++_sp & 255u) == 0u) { if (xb_ld(&(bar)[XB_TMO])) break; if (_sp > XB_SPIN_CAP) { atomicAdd(&(bar)[XB_TMO], 1u); break; } } } } while (0)
; __device__ __forceinline__ void xcd_wait(const XcdBarrier& b, unsigned use) {
;     if (b.w0 != 0 && lane_id() == 0) {
;         unsigned* bar = b.bar;
;         XB_SPIN(xb_ld(&bar[XB_TOPGEN]) <= use, bar);
;         __builtin_amdgcn_fence(__ATOMIC_ACQUIRE, "agent");
;         asm volatile("s_waitcnt vmcnt(0)" ::: "memory");
;     }
.LBB0_427:
	s_and_b64 vcc, exec, s[94:95]
	s_cbranch_vccnz .LBB0_444
	v_mbcnt_lo_u32_b32 v0, -1, 0
	v_mbcnt_hi_u32_b32 v0, -1, v0
	s_nop 0
	v_cmp_eq_u32_e32 vcc, 0, v0
	s_and_saveexec_b64 s[2:3], vcc
	s_cbranch_execz .LBB0_443
	buffer_inv sc1
	v_mov_b32_e32 v0, 0x3000
	global_load_dword v0, v0, s[52:53] offset:1280 sc1
	s_add_u32 s4, s52, 0x3500
	s_addc_u32 s5, s53, 0
	s_mov_b32 s0, 1
	s_waitcnt vmcnt(0)
	v_cmp_lt_u32_e32 vcc, 1, v0
	s_cbranch_vccnz .LBB0_442
	v_mov_b32_e32 v0, 0
	s_branch .LBB0_432
